# SwiGLU epilogue hand-scheduled: (ag*au)*rcp((1+exp2(ag*rs*-log2e))/rs^2) with packed f32 ops, sc1 stores via SGPR base; resid epilogue as v4
# speedup vs baseline: 1.0128x; 1.0128x over previous
.LBB0_360:
	s_or_b64 exec, exec, s[18:19]
	s_waitcnt lgkmcnt(0)
	s_barrier
	ds_read_b32 v174, v148 offset:0
	ds_read_b32 v176, v148 offset:64
	ds_read_b32 v178, v148 offset:128
	ds_read_b32 v180, v148 offset:192
	ds_read_b32 v182, v148 offset:512
	ds_read_b32 v184, v148 offset:576
	ds_read_b32 v186, v148 offset:640
	ds_read_b32 v188, v148 offset:704
	v_readlane_b32 s18, v242, 53
	v_readlane_b32 s19, v242, 54
	v_add_u32_e32 v207, s9, v131
	v_lshl_or_b32 v208, s45, 7, v149
	v_mul_u32_u24_e32 v206, 0x1600, v207
	v_lshl_add_u32 v206, v208, 1, v206
	s_waitcnt lgkmcnt(0)
	v_mul_f32_e32 v190, v174, v174
	v_mul_f32_e32 v192, v176, v176
	v_mul_f32_e32 v194, v178, v178
	v_mul_f32_e32 v196, v180, v180
	v_mul_f32_e32 v198, v182, v182
	v_mul_f32_e32 v200, v184, v184
	v_mul_f32_e32 v202, v186, v186
	v_mul_f32_e32 v204, v188, v188
	v_rcp_f32_e32 v190, v190
	v_rcp_f32_e32 v192, v192
	v_rcp_f32_e32 v194, v194
	v_rcp_f32_e32 v196, v196
	v_rcp_f32_e32 v198, v198
	v_rcp_f32_e32 v200, v200
	v_rcp_f32_e32 v202, v202
	v_rcp_f32_e32 v204, v204
	v_mul_f32_e32 v174, 0xbfb8aa3b, v174
	v_mul_f32_e32 v176, 0xbfb8aa3b, v176
	v_mul_f32_e32 v178, 0xbfb8aa3b, v178
	v_mul_f32_e32 v180, 0xbfb8aa3b, v180
	v_mul_f32_e32 v182, 0xbfb8aa3b, v182
	v_mul_f32_e32 v184, 0xbfb8aa3b, v184
	v_mul_f32_e32 v186, 0xbfb8aa3b, v186
	v_mul_f32_e32 v188, 0xbfb8aa3b, v188
	v_pk_mul_f32 v[152:153], v[124:125], v[174:175] op_sel_hi:[1,0]
	v_pk_mul_f32 v[154:155], v[126:127], v[174:175] op_sel_hi:[1,0]
	v_pk_mul_f32 v[170:171], v[116:117], v[174:175] op_sel_hi:[1,0]
	v_pk_mul_f32 v[172:173], v[118:119], v[174:175] op_sel_hi:[1,0]
	v_exp_f32_e32 v152, v152
	v_exp_f32_e32 v153, v153
	v_exp_f32_e32 v154, v154
	v_exp_f32_e32 v155, v155
	v_exp_f32_e32 v170, v170
	v_exp_f32_e32 v171, v171
	v_exp_f32_e32 v172, v172
	v_exp_f32_e32 v173, v173
	v_pk_mul_f32 v[124:125], v[124:125], v[120:121]
	v_pk_mul_f32 v[126:127], v[126:127], v[122:123]
	v_pk_mul_f32 v[116:117], v[116:117], v[112:113]
	v_pk_mul_f32 v[118:119], v[118:119], v[114:115]
	v_pk_fma_f32 v[152:153], v[152:153], v[190:191], v[190:191] op_sel_hi:[1,0,0]
	v_pk_fma_f32 v[154:155], v[154:155], v[190:191], v[190:191] op_sel_hi:[1,0,0]
	v_pk_fma_f32 v[170:171], v[170:171], v[190:191], v[190:191] op_sel_hi:[1,0,0]
	v_pk_fma_f32 v[172:173], v[172:173], v[190:191], v[190:191] op_sel_hi:[1,0,0]
	v_rcp_f32_e32 v152, v152
	v_rcp_f32_e32 v153, v153
	v_rcp_f32_e32 v154, v154
	v_rcp_f32_e32 v155, v155
	v_rcp_f32_e32 v170, v170
	v_rcp_f32_e32 v171, v171
	v_rcp_f32_e32 v172, v172
	v_rcp_f32_e32 v173, v173
	s_nop 0
	v_pk_mul_f32 v[124:125], v[124:125], v[152:153]
	v_pk_mul_f32 v[126:127], v[126:127], v[154:155]
	v_pk_mul_f32 v[116:117], v[116:117], v[170:171]
	v_pk_mul_f32 v[118:119], v[118:119], v[172:173]
	v_cvt_pk_bf16_f32 v120, v124, v125
	v_cvt_pk_bf16_f32 v121, v126, v127
	v_cvt_pk_bf16_f32 v122, v116, v117
	v_cvt_pk_bf16_f32 v123, v118, v119
	global_store_dwordx4 v206, v[120:123], s[18:19] sc1
	v_add_u32_e32 v206, 0x16000, v206
	v_pk_mul_f32 v[152:153], v[108:109], v[176:177] op_sel_hi:[1,0]
	v_pk_mul_f32 v[154:155], v[110:111], v[176:177] op_sel_hi:[1,0]
	v_pk_mul_f32 v[170:171], v[100:101], v[176:177] op_sel_hi:[1,0]
	v_pk_mul_f32 v[172:173], v[102:103], v[176:177] op_sel_hi:[1,0]
	v_exp_f32_e32 v152, v152
	v_exp_f32_e32 v153, v153
	v_exp_f32_e32 v154, v154
	v_exp_f32_e32 v155, v155
	v_exp_f32_e32 v170, v170
	v_exp_f32_e32 v171, v171
	v_exp_f32_e32 v172, v172
	v_exp_f32_e32 v173, v173
	v_pk_mul_f32 v[108:109], v[108:109], v[104:105]
	v_pk_mul_f32 v[110:111], v[110:111], v[106:107]
	v_pk_mul_f32 v[100:101], v[100:101], v[96:97]
	v_pk_mul_f32 v[102:103], v[102:103], v[98:99]
	v_pk_fma_f32 v[152:153], v[152:153], v[192:193], v[192:193] op_sel_hi:[1,0,0]
	v_pk_fma_f32 v[154:155], v[154:155], v[192:193], v[192:193] op_sel_hi:[1,0,0]
	v_pk_fma_f32 v[170:171], v[170:171], v[192:193], v[192:193] op_sel_hi:[1,0,0]
	v_pk_fma_f32 v[172:173], v[172:173], v[192:193], v[192:193] op_sel_hi:[1,0,0]
	v_rcp_f32_e32 v152, v152
	v_rcp_f32_e32 v153, v153
	v_rcp_f32_e32 v154, v154
	v_rcp_f32_e32 v155, v155
	v_rcp_f32_e32 v170, v170
	v_rcp_f32_e32 v171, v171
	v_rcp_f32_e32 v172, v172
	v_rcp_f32_e32 v173, v173
	s_nop 0
	v_pk_mul_f32 v[108:109], v[108:109], v[152:153]
	v_pk_mul_f32 v[110:111], v[110:111], v[154:155]
	v_pk_mul_f32 v[100:101], v[100:101], v[170:171]
	v_pk_mul_f32 v[102:103], v[102:103], v[172:173]
	v_cvt_pk_bf16_f32 v104, v108, v109
	v_cvt_pk_bf16_f32 v105, v110, v111
	v_cvt_pk_bf16_f32 v106, v100, v101
	v_cvt_pk_bf16_f32 v107, v102, v103
	global_store_dwordx4 v206, v[104:107], s[18:19] sc1
	v_add_u32_e32 v206, 0x16000, v206
	v_pk_mul_f32 v[152:153], v[92:93], v[178:179] op_sel_hi:[1,0]
	v_pk_mul_f32 v[154:155], v[94:95], v[178:179] op_sel_hi:[1,0]
	v_pk_mul_f32 v[170:171], v[84:85], v[178:179] op_sel_hi:[1,0]
	v_pk_mul_f32 v[172:173], v[86:87], v[178:179] op_sel_hi:[1,0]
	v_exp_f32_e32 v152, v152
	v_exp_f32_e32 v153, v153
	v_exp_f32_e32 v154, v154
	v_exp_f32_e32 v155, v155
	v_exp_f32_e32 v170, v170
	v_exp_f32_e32 v171, v171
	v_exp_f32_e32 v172, v172
	v_exp_f32_e32 v173, v173
	v_pk_mul_f32 v[92:93], v[92:93], v[88:89]
	v_pk_mul_f32 v[94:95], v[94:95], v[90:91]
	v_pk_mul_f32 v[84:85], v[84:85], v[80:81]
	v_pk_mul_f32 v[86:87], v[86:87], v[82:83]
	v_pk_fma_f32 v[152:153], v[152:153], v[194:195], v[194:195] op_sel_hi:[1,0,0]
	v_pk_fma_f32 v[154:155], v[154:155], v[194:195], v[194:195] op_sel_hi:[1,0,0]
	v_pk_fma_f32 v[170:171], v[170:171], v[194:195], v[194:195] op_sel_hi:[1,0,0]
	v_pk_fma_f32 v[172:173], v[172:173], v[194:195], v[194:195] op_sel_hi:[1,0,0]
	v_rcp_f32_e32 v152, v152
	v_rcp_f32_e32 v153, v153
	v_rcp_f32_e32 v154, v154
	v_rcp_f32_e32 v155, v155
	v_rcp_f32_e32 v170, v170
	v_rcp_f32_e32 v171, v171
	v_rcp_f32_e32 v172, v172
	v_rcp_f32_e32 v173, v173
	s_nop 0
	v_pk_mul_f32 v[92:93], v[92:93], v[152:153]
	v_pk_mul_f32 v[94:95], v[94:95], v[154:155]
	v_pk_mul_f32 v[84:85], v[84:85], v[170:171]
	v_pk_mul_f32 v[86:87], v[86:87], v[172:173]
	v_cvt_pk_bf16_f32 v88, v92, v93
	v_cvt_pk_bf16_f32 v89, v94, v95
	v_cvt_pk_bf16_f32 v90, v84, v85
	v_cvt_pk_bf16_f32 v91, v86, v87
	global_store_dwordx4 v206, v[88:91], s[18:19] sc1
	v_add_u32_e32 v206, 0x16000, v206
	v_pk_mul_f32 v[152:153], v[76:77], v[180:181] op_sel_hi:[1,0]
	v_pk_mul_f32 v[154:155], v[78:79], v[180:181] op_sel_hi:[1,0]
	v_pk_mul_f32 v[170:171], v[68:69], v[180:181] op_sel_hi:[1,0]
	v_pk_mul_f32 v[172:173], v[70:71], v[180:181] op_sel_hi:[1,0]
	v_exp_f32_e32 v152, v152
	v_exp_f32_e32 v153, v153
	v_exp_f32_e32 v154, v154
	v_exp_f32_e32 v155, v155
	v_exp_f32_e32 v170, v170
	v_exp_f32_e32 v171, v171
	v_exp_f32_e32 v172, v172
	v_exp_f32_e32 v173, v173
	v_pk_mul_f32 v[76:77], v[76:77], v[72:73]
	v_pk_mul_f32 v[78:79], v[78:79], v[74:75]
	v_pk_mul_f32 v[68:69], v[68:69], v[64:65]
	v_pk_mul_f32 v[70:71], v[70:71], v[66:67]
	v_pk_fma_f32 v[152:153], v[152:153], v[196:197], v[196:197] op_sel_hi:[1,0,0]
	v_pk_fma_f32 v[154:155], v[154:155], v[196:197], v[196:197] op_sel_hi:[1,0,0]
	v_pk_fma_f32 v[170:171], v[170:171], v[196:197], v[196:197] op_sel_hi:[1,0,0]
	v_pk_fma_f32 v[172:173], v[172:173], v[196:197], v[196:197] op_sel_hi:[1,0,0]
	v_rcp_f32_e32 v152, v152
	v_rcp_f32_e32 v153, v153
	v_rcp_f32_e32 v154, v154
	v_rcp_f32_e32 v155, v155
	v_rcp_f32_e32 v170, v170
	v_rcp_f32_e32 v171, v171
	v_rcp_f32_e32 v172, v172
	v_rcp_f32_e32 v173, v173
	s_nop 0
	v_pk_mul_f32 v[76:77], v[76:77], v[152:153]
	v_pk_mul_f32 v[78:79], v[78:79], v[154:155]
	v_pk_mul_f32 v[68:69], v[68:69], v[170:171]
	v_pk_mul_f32 v[70:71], v[70:71], v[172:173]
	v_cvt_pk_bf16_f32 v72, v76, v77
	v_cvt_pk_bf16_f32 v73, v78, v79
	v_cvt_pk_bf16_f32 v74, v68, v69
	v_cvt_pk_bf16_f32 v75, v70, v71
	global_store_dwordx4 v206, v[72:75], s[18:19] sc1
	v_add_u32_e32 v206, 0x6e000, v206
	v_pk_mul_f32 v[152:153], v[60:61], v[182:183] op_sel_hi:[1,0]
	v_pk_mul_f32 v[154:155], v[62:63], v[182:183] op_sel_hi:[1,0]
	v_pk_mul_f32 v[170:171], v[52:53], v[182:183] op_sel_hi:[1,0]
	v_pk_mul_f32 v[172:173], v[54:55], v[182:183] op_sel_hi:[1,0]
	v_exp_f32_e32 v152, v152
	v_exp_f32_e32 v153, v153
	v_exp_f32_e32 v154, v154
	v_exp_f32_e32 v155, v155
	v_exp_f32_e32 v170, v170
	v_exp_f32_e32 v171, v171
	v_exp_f32_e32 v172, v172
	v_exp_f32_e32 v173, v173
	v_pk_mul_f32 v[60:61], v[60:61], v[56:57]
	v_pk_mul_f32 v[62:63], v[62:63], v[58:59]
	v_pk_mul_f32 v[52:53], v[52:53], v[48:49]
	v_pk_mul_f32 v[54:55], v[54:55], v[50:51]
	v_pk_fma_f32 v[152:153], v[152:153], v[198:199], v[198:199] op_sel_hi:[1,0,0]
	v_pk_fma_f32 v[154:155], v[154:155], v[198:199], v[198:199] op_sel_hi:[1,0,0]
	v_pk_fma_f32 v[170:171], v[170:171], v[198:199], v[198:199] op_sel_hi:[1,0,0]
	v_pk_fma_f32 v[172:173], v[172:173], v[198:199], v[198:199] op_sel_hi:[1,0,0]
	v_rcp_f32_e32 v152, v152
	v_rcp_f32_e32 v153, v153
	v_rcp_f32_e32 v154, v154
	v_rcp_f32_e32 v155, v155
	v_rcp_f32_e32 v170, v170
	v_rcp_f32_e32 v171, v171
	v_rcp_f32_e32 v172, v172
	v_rcp_f32_e32 v173, v173
	s_nop 0
	v_pk_mul_f32 v[60:61], v[60:61], v[152:153]
	v_pk_mul_f32 v[62:63], v[62:63], v[154:155]
	v_pk_mul_f32 v[52:53], v[52:53], v[170:171]
	v_pk_mul_f32 v[54:55], v[54:55], v[172:173]
	v_cvt_pk_bf16_f32 v56, v60, v61
	v_cvt_pk_bf16_f32 v57, v62, v63
	v_cvt_pk_bf16_f32 v58, v52, v53
	v_cvt_pk_bf16_f32 v59, v54, v55
	global_store_dwordx4 v206, v[56:59], s[18:19] sc1
	v_add_u32_e32 v206, 0x16000, v206
	v_pk_mul_f32 v[152:153], v[44:45], v[184:185] op_sel_hi:[1,0]
	v_pk_mul_f32 v[154:155], v[46:47], v[184:185] op_sel_hi:[1,0]
	v_pk_mul_f32 v[170:171], v[36:37], v[184:185] op_sel_hi:[1,0]
	v_pk_mul_f32 v[172:173], v[38:39], v[184:185] op_sel_hi:[1,0]
	v_exp_f32_e32 v152, v152
	v_exp_f32_e32 v153, v153
	v_exp_f32_e32 v154, v154
	v_exp_f32_e32 v155, v155
	v_exp_f32_e32 v170, v170
	v_exp_f32_e32 v171, v171
	v_exp_f32_e32 v172, v172
	v_exp_f32_e32 v173, v173
	v_pk_mul_f32 v[44:45], v[44:45], v[40:41]
	v_pk_mul_f32 v[46:47], v[46:47], v[42:43]
	v_pk_mul_f32 v[36:37], v[36:37], v[32:33]
	v_pk_mul_f32 v[38:39], v[38:39], v[34:35]
	v_pk_fma_f32 v[152:153], v[152:153], v[200:201], v[200:201] op_sel_hi:[1,0,0]
	v_pk_fma_f32 v[154:155], v[154:155], v[200:201], v[200:201] op_sel_hi:[1,0,0]
	v_pk_fma_f32 v[170:171], v[170:171], v[200:201], v[200:201] op_sel_hi:[1,0,0]
	v_pk_fma_f32 v[172:173], v[172:173], v[200:201], v[200:201] op_sel_hi:[1,0,0]
	v_rcp_f32_e32 v152, v152
	v_rcp_f32_e32 v153, v153
	v_rcp_f32_e32 v154, v154
	v_rcp_f32_e32 v155, v155
	v_rcp_f32_e32 v170, v170
	v_rcp_f32_e32 v171, v171
	v_rcp_f32_e32 v172, v172
	v_rcp_f32_e32 v173, v173
	s_nop 0
	v_pk_mul_f32 v[44:45], v[44:45], v[152:153]
	v_pk_mul_f32 v[46:47], v[46:47], v[154:155]
	v_pk_mul_f32 v[36:37], v[36:37], v[170:171]
	v_pk_mul_f32 v[38:39], v[38:39], v[172:173]
	v_cvt_pk_bf16_f32 v40, v44, v45
	v_cvt_pk_bf16_f32 v41, v46, v47
	v_cvt_pk_bf16_f32 v42, v36, v37
	v_cvt_pk_bf16_f32 v43, v38, v39
	global_store_dwordx4 v206, v[40:43], s[18:19] sc1
	v_add_u32_e32 v206, 0x16000, v206
	v_pk_mul_f32 v[152:153], v[28:29], v[186:187] op_sel_hi:[1,0]
	v_pk_mul_f32 v[154:155], v[30:31], v[186:187] op_sel_hi:[1,0]
	v_pk_mul_f32 v[170:171], v[20:21], v[186:187] op_sel_hi:[1,0]
	v_pk_mul_f32 v[172:173], v[22:23], v[186:187] op_sel_hi:[1,0]
	v_exp_f32_e32 v152, v152
	v_exp_f32_e32 v153, v153
	v_exp_f32_e32 v154, v154
	v_exp_f32_e32 v155, v155
	v_exp_f32_e32 v170, v170
	v_exp_f32_e32 v171, v171
	v_exp_f32_e32 v172, v172
	v_exp_f32_e32 v173, v173
	v_pk_mul_f32 v[28:29], v[28:29], v[24:25]
	v_pk_mul_f32 v[30:31], v[30:31], v[26:27]
	v_pk_mul_f32 v[20:21], v[20:21], v[16:17]
	v_pk_mul_f32 v[22:23], v[22:23], v[18:19]
	v_pk_fma_f32 v[152:153], v[152:153], v[202:203], v[202:203] op_sel_hi:[1,0,0]
	v_pk_fma_f32 v[154:155], v[154:155], v[202:203], v[202:203] op_sel_hi:[1,0,0]
	v_pk_fma_f32 v[170:171], v[170:171], v[202:203], v[202:203] op_sel_hi:[1,0,0]
	v_pk_fma_f32 v[172:173], v[172:173], v[202:203], v[202:203] op_sel_hi:[1,0,0]
	v_rcp_f32_e32 v152, v152
	v_rcp_f32_e32 v153, v153
	v_rcp_f32_e32 v154, v154
	v_rcp_f32_e32 v155, v155
	v_rcp_f32_e32 v170, v170
	v_rcp_f32_e32 v171, v171
	v_rcp_f32_e32 v172, v172
	v_rcp_f32_e32 v173, v173
	s_nop 0
	v_pk_mul_f32 v[28:29], v[28:29], v[152:153]
	v_pk_mul_f32 v[30:31], v[30:31], v[154:155]
	v_pk_mul_f32 v[20:21], v[20:21], v[170:171]
	v_pk_mul_f32 v[22:23], v[22:23], v[172:173]
	v_cvt_pk_bf16_f32 v24, v28, v29
	v_cvt_pk_bf16_f32 v25, v30, v31
	v_cvt_pk_bf16_f32 v26, v20, v21
	v_cvt_pk_bf16_f32 v27, v22, v23
	global_store_dwordx4 v206, v[24:27], s[18:19] sc1
	v_add_u32_e32 v206, 0x16000, v206
	v_pk_mul_f32 v[152:153], v[12:13], v[188:189] op_sel_hi:[1,0]
	v_pk_mul_f32 v[154:155], v[14:15], v[188:189] op_sel_hi:[1,0]
	v_pk_mul_f32 v[170:171], v[4:5], v[188:189] op_sel_hi:[1,0]
	v_pk_mul_f32 v[172:173], v[6:7], v[188:189] op_sel_hi:[1,0]
	v_exp_f32_e32 v152, v152
	v_exp_f32_e32 v153, v153
	v_exp_f32_e32 v154, v154
	v_exp_f32_e32 v155, v155
	v_exp_f32_e32 v170, v170
	v_exp_f32_e32 v171, v171
	v_exp_f32_e32 v172, v172
	v_exp_f32_e32 v173, v173
	v_pk_mul_f32 v[12:13], v[12:13], v[8:9]
	v_pk_mul_f32 v[14:15], v[14:15], v[10:11]
	v_pk_mul_f32 v[4:5], v[4:5], v[0:1]
	v_pk_mul_f32 v[6:7], v[6:7], v[2:3]
	v_pk_fma_f32 v[152:153], v[152:153], v[204:205], v[204:205] op_sel_hi:[1,0,0]
	v_pk_fma_f32 v[154:155], v[154:155], v[204:205], v[204:205] op_sel_hi:[1,0,0]
	v_pk_fma_f32 v[170:171], v[170:171], v[204:205], v[204:205] op_sel_hi:[1,0,0]
	v_pk_fma_f32 v[172:173], v[172:173], v[204:205], v[204:205] op_sel_hi:[1,0,0]
	v_rcp_f32_e32 v152, v152
	v_rcp_f32_e32 v153, v153
	v_rcp_f32_e32 v154, v154
	v_rcp_f32_e32 v155, v155
	v_rcp_f32_e32 v170, v170
	v_rcp_f32_e32 v171, v171
	v_rcp_f32_e32 v172, v172
	v_rcp_f32_e32 v173, v173
	s_nop 0
	v_pk_mul_f32 v[12:13], v[12:13], v[152:153]
	v_pk_mul_f32 v[14:15], v[14:15], v[154:155]
	v_pk_mul_f32 v[4:5], v[4:5], v[170:171]
	v_pk_mul_f32 v[6:7], v[6:7], v[172:173]
	v_cvt_pk_bf16_f32 v8, v12, v13
	v_cvt_pk_bf16_f32 v9, v14, v15
	v_cvt_pk_bf16_f32 v10, v4, v5
	v_cvt_pk_bf16_f32 v11, v6, v7
	global_store_dwordx4 v206, v[8:11], s[18:19] sc1
	s_andn2_b64 vcc, exec, s[12:13]
	s_nop 0
	s_mov_b64 s[18:19], -1
	s_cbranch_vccnz .LBB0_351
	s_andn2_b64 vcc, exec, s[0:1]
	s_cbranch_vccnz .LBB0_350
	s_barrier
	s_branch .LBB0_350
